# P7 conv-first group chosen by blockIdx bit 0 (XCD parity) instead of bit 3, on top of k3
# baseline (speedup 1.0000x reference)
; __device__ __forceinline__ void mixer_phase(Frame& F, const Args& A) {
;     ...
;     for (int u = F.vcu; u < 256 * (PROBE_P7 == 1 ? 2 : 1); u += F.G) prompt_unit(F, A, (u & 255) >> 2, u & 3);
;     for (int u = F.vcu; u < 512 * (PROBE_P7 == 2 ? 2 : 1); u += F.G) sample_unit(F, A, (u & 511) >> 2, u & 3);
;     for (int u = F.vcu * NWAVES + F.wave; u < (M / 8) * 8 * (PROBE_P7 == 3 ? 2 : 1); u += F.G * NWAVES) conv_item(F, A, u % ((M / 8) * 8));
.Lp7_again:
	s_cmpk_eq_i32 s33, 0x100
	s_cbranch_scc0 .Lp7_norm
	s_cmp_eq_u32 s101, 7
	s_cbranch_scc1 .Lp7_norm
	s_bitcmp1_b32 s50, 0
	s_cbranch_scc0 .Lp7_norm
	v_writelane_b32 v253, s17, 0
	v_writelane_b32 v253, s18, 1
	v_writelane_b32 v253, s19, 2
	v_writelane_b32 v253, s20, 3
	v_writelane_b32 v253, s21, 4
	v_writelane_b32 v253, s22, 5
	v_writelane_b32 v253, s23, 6
	v_writelane_b32 v253, s48, 7
	v_writelane_b32 v253, s54, 8
	v_writelane_b32 v253, s58, 9
	v_writelane_b32 v253, s59, 10
	v_writelane_b32 v253, s60, 11
	v_writelane_b32 v253, s61, 12
	v_writelane_b32 v253, s62, 13
	v_writelane_b32 v253, s63, 14
	v_writelane_b32 v253, s66, 15
	v_writelane_b32 v253, s67, 16
	v_writelane_b32 v253, s88, 17
	v_writelane_b32 v253, s94, 18
	v_writelane_b32 v253, s95, 19
	v_writelane_b32 v253, s96, 20
	v_writelane_b32 v253, s97, 21
	v_mov_b32_e32 v223, v14
	v_mov_b32_e32 v224, v15
	v_mov_b32_e32 v225, v16
	v_mov_b32_e32 v226, v17
	v_mov_b32_e32 v227, v18
	v_mov_b32_e32 v228, v19
	v_mov_b32_e32 v229, v20
	v_mov_b32_e32 v230, v21
	v_mov_b32_e32 v231, v25
	s_mov_b32 s101, 6
	s_mov_b64 s[36:37], s[96:97]
	s_mov_b64 s[38:39], s[58:59]
	s_mov_b64 s[44:45], s[94:95]
	s_branch .LBB0_641
